# output-pass job order: each block runs the forward then the backward scan of the same tokens (sample segment g / 7-g; context fwd / bwd), forward stores y, only the backward accumulates; no Ysum zeroi
# speedup vs baseline: 1.0090x; 1.0090x over previous
.LBB0_901:
	s_or_b64 exec, exec, s[6:7]
	s_waitcnt lgkmcnt(0)
	s_load_dword s3, s[0:1], 0x108
	v_cmp_lt_i32_e32 vcc, 9, v10
	s_waitcnt lgkmcnt(0)
	s_cmp_lt_i32 s3, 11
	s_cselect_b64 s[6:7], -1, 0
	s_and_b64 s[6:7], s[6:7], vcc
	s_and_saveexec_b64 s[12:13], s[6:7]
	s_cbranch_execz .LBB0_1097
	s_cmpk_gt_u32 s2, 0x1bf
	s_mov_b64 s[6:7], -1
	s_cbranch_scc0 .LBB0_914
	s_load_dwordx2 s[10:11], s[0:1], 0x100
	s_load_dword s30, s[0:1], 0x640
	s_add_i32 s6, s2, 0xfffffe40
	s_mov_b32 s7, 0
	v_mov_b32_e32 v2, 0
	s_lshl_b64 s[8:9], s[6:7], 8
	v_mov_b32_e32 v177, v2
	v_lshl_add_u64 v[6:7], s[8:9], 0, v[176:177]
	s_waitcnt lgkmcnt(0)
	s_add_i32 s8, s30, 0xfffffe40
	s_mov_b32 s9, s7
	s_mov_b64 s[16:17], 0
	s_lshl_b64 s[14:15], s[8:9], 8
	v_cmp_gt_u64_e32 vcc, s[16:17], v[6:7]
	v_lshlrev_b32_e32 v0, 4, v176
	s_and_saveexec_b64 s[16:17], vcc
	s_cbranch_execz .LBB0_906
	s_lshl_b64 s[18:19], s[6:7], 12
	s_add_u32 s18, s10, s18
	v_mov_b32_e32 v1, v2
	s_addc_u32 s19, s11, s19
	v_lshl_add_u64 v[4:5], s[18:19], 0, v[0:1]
	s_mov_b64 s[18:19], 0xa200000
	v_lshl_add_u64 v[8:9], v[4:5], 0, s[18:19]
	s_lshl_b64 s[18:19], s[8:9], 12
	s_mov_b64 s[20:21], 0
	v_mov_b32_e32 v3, v2
	v_mov_b32_e32 v4, v2
	v_mov_b32_e32 v5, v2
	s_mov_b64 s[26:27], 0x3fffff
	v_mov_b64_e32 v[10:11], v[6:7]

.LBB0_1097:
	s_or_b64 exec, exec, s[12:13]
	s_load_dword s3, s[0:1], 0x108
	v_cmp_lt_i32_e32 vcc, 10, v10
	s_waitcnt lgkmcnt(0)
	s_cmp_lt_i32 s3, 12
	s_cselect_b64 s[6:7], -1, 0
	s_and_b64 s[6:7], s[6:7], vcc
	s_and_saveexec_b64 s[20:21], s[6:7]
	s_cbranch_execz .LBB0_1402
	s_cmpk_gt_i32 s2, 0x5ff
	s_cbranch_scc1 .LBB0_1347
	s_load_dwordx4 s[12:15], s[0:1], 0xf8
	s_add_u32 s26, s0, 0x640
	s_addc_u32 s27, s1, 0
	v_bfe_u32 v2, v176, 5, 1
	s_waitcnt vmcnt(12)
	v_and_b32_e32 v135, 31, v176
	s_waitcnt lgkmcnt(0)
	s_add_u32 s3, s12, 0x6000000
	s_addc_u32 s43, s13, 0
	s_add_u32 s30, s14, 0x4200000
	s_addc_u32 s31, s15, 0
	s_add_u32 s62, s14, 0xa200000
	s_addc_u32 s63, s15, 0
	s_add_u32 s34, s14, 0x2200000
	v_lshlrev_b32_e32 v0, 3, v2
	s_load_dwordx2 s[28:29], s[0:1], 0xd8
	s_addc_u32 s35, s15, 0
	s_load_dwordx4 s[16:19], s[0:1], 0xc8
	s_load_dwordx2 s[38:39], s[0:1], 0x20
	s_add_u32 s36, s14, 0x6200000
	s_waitcnt vmcnt(11)
	v_lshl_or_b32 v136, v135, 7, v0
	s_waitcnt vmcnt(10)
	v_lshlrev_b32_e32 v140, 1, v0
	v_mbcnt_lo_u32_b32 v0, -1, 0
	v_lshlrev_b32_e32 v3, 3, v176
	s_addc_u32 s37, s15, 0
	v_mbcnt_hi_u32_b32 v152, -1, v0
	v_mov_b32_e32 v1, 0
	v_lshlrev_b32_e32 v137, 2, v176
	s_waitcnt vmcnt(8)
	v_and_b32_e32 v147, 56, v3
	v_lshrrev_b32_e32 v148, 3, v176
	s_add_u32 s64, s14, 0x100000
	v_mov_b32_e32 v3, 0x600080
	v_and_b32_e32 v0, 64, v152
	v_cmp_gt_u32_e64 s[6:7], 64, v176
	v_lshlrev_b32_e32 v146, 6, v135
	v_lshlrev_b32_e32 v134, 2, v2
	v_bitop3_b32 v149, v176, 31, v176 bitop3:0xc
	v_sub_u32_e32 v150, 31, v148
	s_addc_u32 s65, s15, 0
	v_lshl_or_b32 v138, v2, 4, v3
	v_mov_b32_e32 v139, v1
	s_mov_b32 s66, 0xf7c0000
	s_mov_b32 s41, 0
	s_movk_i32 s67, 0x88
	s_mov_b32 s68, 0xf880000
	s_movk_i32 s69, 0x4100
	s_movk_i32 s70, 0x6500
	s_mov_b32 s71, 0xcfc0
	s_mov_b32 s42, 0xbf1b459e
	s_movk_i32 s72, 0x104
	s_mov_b32 s73, 0x800000
	s_movk_i32 s74, 0x140
	s_movk_i32 s75, 0x90
	s_movk_i32 s76, 0x84
	s_movk_i32 s77, 0x50
	s_movk_i32 s78, 0x44
	s_mov_b32 s79, 0x200000
	s_mov_b32 s80, 0x201000
	s_mov_b64 s[44:45], 0x2000
	s_mov_b64 s[46:47], 0x4000
	v_add_u32_e32 v151, 0xc0, v137
	v_xor_b32_e32 v153, 32, v152
	v_add_u32_e32 v154, 64, v0
	v_mov_b32_e32 v155, 0x3540
	v_mov_b32_e32 v156, 0x3100
	s_cmpk_lt_u32 s2, 0x100
	s_cselect_b32 s81, 0, 0x100
	s_add_i32 s81, s81, s2
	s_branch .LBB0_1102

.LBB0_1101:
	s_waitcnt lgkmcnt(0)
	s_cmpk_lt_u32 s81, 0x100
	s_cbranch_scc1 .Ljn_s1
	s_cmpk_lt_u32 s81, 0x200
	s_cbranch_scc1 .LBB0_1346
	s_cmpk_ge_u32 s81, 0x500
	s_cbranch_scc1 .LBB0_1346
	s_movk_i32 s8, 0x200
	s_cmpk_ge_u32 s81, 0x400
	s_cselect_b32 s8, 0xffffff00, s8
	s_add_i32 s81, s81, s8
	s_branch .LBB0_1102
.Ljn_s1:
	s_xor_b32 s81, s2, 7
	s_addk_i32 s81, 0x100

.Le23_skip_c:
	s_waitcnt lgkmcnt(0)
	s_barrier
	s_andn2_b64 vcc, exec, s[8:9]
	s_cbranch_vccnz .LBB0_1235
	v_lshlrev_b32_e32 v80, 1, v0
	v_add_u32_e32 v46, v66, v80
	v_add_u32_e32 v47, 0x4000, v46
	ds_read2_b64 v[34:37], v47 offset0:32 offset1:34
	v_cvt_pk_bf16_f32 v38, v18, v19
	v_cvt_pk_bf16_f32 v39, v20, v21
	v_cvt_pk_bf16_f32 v40, v22, v23
	v_cvt_pk_bf16_f32 v41, v24, v25
	ds_read2_b64 v[42:45], v47 offset0:36 offset1:38
	v_lshlrev_b32_e32 v48, 3, v51
	v_cvt_pk_bf16_f32 v72, v26, v27
	v_cvt_pk_bf16_f32 v73, v28, v29
	s_waitcnt lgkmcnt(1)
	v_mfma_f32_32x32x16_bf16 v[50:65], v[34:37], v[38:41], 0
	v_cvt_pk_bf16_f32 v74, v30, v31
	v_cvt_pk_bf16_f32 v75, v32, v33
	ds_read2_b64 v[34:37], v47 offset0:40 offset1:42
	v_cvt_pk_bf16_f32 v76, v2, v3
	v_cvt_pk_bf16_f32 v77, v4, v5
	v_cvt_pk_bf16_f32 v78, v6, v7
	v_cvt_pk_bf16_f32 v79, v8, v9
	s_waitcnt lgkmcnt(1)
	v_mfma_f32_32x32x16_bf16 v[50:65], v[42:45], v[72:75], v[50:65]
	ds_read2_b64 v[42:45], v47 offset0:44 offset1:46
	v_cvt_pk_bf16_f32 v172, v10, v11
	v_cvt_pk_bf16_f32 v173, v12, v13
	v_cvt_pk_bf16_f32 v174, v14, v15
	v_cvt_pk_bf16_f32 v175, v16, v17
	v_mov_b32_e32 v49, s88
	v_bitop3_b32 v47, v48, v141, 24 bitop3:0x78
	s_waitcnt lgkmcnt(1)
	v_mfma_f32_32x32x16_bf16 v[50:65], v[34:37], v[76:79], v[50:65]
	v_lshlrev_b32_e32 v34, 6, v70
	v_sub_u32_e32 v177, v66, v34
	v_lshl_add_u32 v70, v48, 1, v177
	ds_read_b128 v[34:37], v70 offset:50624
	v_mad_u32_u24 v49, v71, s77, v49
	v_lshlrev_b32_e32 v207, 1, v47
	v_and_b32_e32 v145, 24, v141
	s_waitcnt lgkmcnt(1)
	v_mfma_f32_32x32x16_bf16 v[50:65], v[42:45], v[172:175], v[50:65]
	v_add_u32_e32 v42, v49, v207
	ds_read_b128 v[130:133], v42 offset:45440
	v_bitop3_b32 v67, v48, v145, 16 bitop3:0x36
	v_lshlrev_b32_e32 v212, 1, v67
	v_add_u32_e32 v71, 0x5000, v46
	v_add_u32_e32 v47, v49, v212
	ds_read_b128 v[42:45], v70 offset:50656
	ds_read_b128 v[126:129], v47 offset:45440
	s_waitcnt lgkmcnt(2)
	v_mfma_f32_32x32x16_bf16 v[50:65], v[34:37], v[130:133], v[50:65]
	ds_read2_b64 v[34:37], v71 offset0:96 offset1:98
	ds_read2_b64 v[66:69], v71 offset0:100 offset1:102
	ds_read2_b64 v[178:181], v71 offset0:104 offset1:106
	ds_read2_b64 v[182:185], v71 offset0:108 offset1:110
	ds_read_b128 v[186:189], v70 offset:55744
	ds_read_b128 v[190:193], v70 offset:55776
	v_lshlrev_b32_e32 v81, 2, v0
	s_add_i32 s58, s89, 32
	s_and_b64 s[12:13], s[10:11], exec
	s_cselect_b32 s12, s91, s58
	s_waitcnt lgkmcnt(6)
	v_mfma_f32_32x32x16_bf16 v[50:65], v[42:45], v[126:129], v[50:65]
	s_add_i32 s12, s12, s83
	s_waitcnt lgkmcnt(5)
	v_mfma_f32_32x32x16_bf16 v[34:49], v[34:37], v[38:41], 0
	s_nop 8
	v_cvt_pk_bf16_f32 v50, v50, v51
	v_cvt_pk_bf16_f32 v51, v52, v53
	v_cvt_pk_bf16_f32 v52, v54, v55
	v_cvt_pk_bf16_f32 v53, v56, v57
	s_waitcnt lgkmcnt(4)
	v_mfma_f32_32x32x16_bf16 v[34:49], v[66:69], v[72:75], v[34:49]
	ds_read_b128 v[66:69], v81 offset:60928
	ds_read_b128 v[70:73], v81 offset:60960
	ds_read_b128 v[194:197], v81 offset:60864
	ds_read_b128 v[198:201], v81 offset:60896
	ds_read_b128 v[202:205], v81 offset:60992
	ds_read_b128 v[208:211], v81 offset:61024
	s_waitcnt lgkmcnt(4)
	v_pk_mul_f32 v[30:31], v[30:31], v[70:71]
	v_pk_mul_f32 v[26:27], v[26:27], v[66:67]
	v_pk_mul_f32 v[32:33], v[32:33], v[72:73]
	v_pk_mul_f32 v[28:29], v[28:29], v[68:69]
	ds_read_b128 v[66:69], v81 offset:61056
	ds_read_b128 v[70:73], v81 offset:61088
	s_waitcnt lgkmcnt(4)
	v_pk_mul_f32 v[22:23], v[22:23], v[198:199]
	v_mfma_f32_32x32x16_bf16 v[34:49], v[178:181], v[76:79], v[34:49]
	v_mul_f32_e64 v24, v24, v200
	v_mul_f32_e64 v25, v25, v201
	s_waitcnt lgkmcnt(1)
	v_mul_f32_e64 v10, v10, v66
	v_mul_f32_e64 v11, v11, v67
	s_waitcnt lgkmcnt(0)
	v_pk_mul_f32 v[14:15], v[14:15], v[70:71]
	v_pk_mul_f32 v[16:17], v[16:17], v[72:73]
	v_pk_mul_f32 v[12:13], v[12:13], v[68:69]
	v_pk_mul_f32 v[20:21], v[20:21], v[196:197]
	v_pk_mul_f32 v[18:19], v[18:19], v[194:195]
	v_mfma_f32_32x32x16_bf16 v[34:49], v[182:185], v[172:175], v[34:49]
	v_add_u32_e32 v172, v177, v80
	v_add_u32_e32 v66, 0xe000, v172
	ds_read2_b64 v[74:77], v66 offset0:120 offset1:122
	ds_read2_b64 v[54:57], v66 offset0:124 offset1:126
	v_mul_f32_e64 v6, v6, v208
	v_mul_f32_e64 v7, v7, v209
	v_pk_mul_f32 v[8:9], v[8:9], v[210:211]
	v_pk_mul_f32 v[4:5], v[4:5], v[204:205]
	s_waitcnt lgkmcnt(1)
	v_mfma_f32_32x32x16_bf16 v[66:81], v[74:77], v[50:53], 0
	v_cvt_pk_bf16_f32 v50, v58, v59
	v_cvt_pk_bf16_f32 v51, v60, v61
	v_cvt_pk_bf16_f32 v52, v62, v63
	v_cvt_pk_bf16_f32 v53, v64, v65
	v_add_u32_e32 v62, v177, v212
	v_pk_mul_f32 v[2:3], v[2:3], v[202:203]
	s_waitcnt lgkmcnt(0)
	v_mfma_f32_32x32x16_bf16 v[66:81], v[54:57], v[50:53], v[66:81]
	v_add_u32_e32 v54, v177, v207
	ds_read_b128 v[50:53], v54 offset:40256
	ds_read_b128 v[54:57], v54 offset:42880
	ds_read_b128 v[58:61], v62 offset:40256
	ds_read_b128 v[62:65], v62 offset:42880
	s_nop 6
	v_cvt_pk_bf16_f32 v66, v66, v67
	v_mfma_f32_32x32x16_bf16 v[34:49], v[186:189], v[130:133], v[34:49]
	v_cvt_pk_bf16_f32 v67, v68, v69
	v_cvt_pk_bf16_f32 v68, v70, v71
	v_cvt_pk_bf16_f32 v69, v72, v73
	v_cvt_pk_bf16_f32 v70, v74, v75
	v_cvt_pk_bf16_f32 v72, v78, v79
	v_add_u32_e32 v78, 0xc800, v172
	v_lshl_add_u32 v74, v145, 1, v172
	s_waitcnt lgkmcnt(3)
	v_mfma_f32_32x32x16_bf16 v[18:33], v[50:53], v[130:133], v[18:33]
	v_bitop3_b32 v50, v141, 8, 24 bitop3:0x6c
	v_lshl_add_u32 v75, v50, 1, v172
	v_bitop3_b32 v50, v141, 16, 24 bitop3:0x6c
	v_lshl_add_u32 v145, v50, 1, v172
	ds_read2_b64 v[50:53], v78 offset0:248 offset1:250
	v_cvt_pk_bf16_f32 v71, v76, v77
	v_cvt_pk_bf16_f32 v73, v80, v81
	v_mfma_f32_32x32x16_bf16 v[34:49], v[190:193], v[126:129], v[34:49]
	s_waitcnt lgkmcnt(0)
	v_mfma_f32_32x32x16_bf16 v[34:49], v[50:53], v[66:69], v[34:49]
	v_mfma_f32_32x32x16_bf16 v[18:33], v[58:61], v[126:129], v[18:33]
	v_bitop3_b32 v58, v141, 24, v141 bitop3:0xc
	v_lshl_add_u32 v141, v58, 1, v172
	ds_read_b64 v[58:59], v74 offset:35072
	ds_read_b64 v[60:61], v75 offset:35072
	ds_read_b64 v[76:77], v75 offset:37696
	ds_read_b64 v[74:75], v74 offset:37696
	ds_read2_b64 v[78:81], v78 offset0:252 offset1:254
	ds_read_b64 v[50:51], v145 offset:35072
	ds_read_b64 v[52:53], v141 offset:35072
	ds_read_b64 v[174:175], v141 offset:37696
	ds_read_b64 v[172:173], v145 offset:37696
	v_xor_b32_e32 v141, 31, v0
	v_cndmask_b32_e64 v141, v141, v0, s[10:11]
	s_waitcnt lgkmcnt(4)
	v_mfma_f32_32x32x16_bf16 v[34:49], v[78:81], v[70:73], v[34:49]
	v_or_b32_e32 v78, s12, v141
	v_lshl_add_u32 v78, v78, 12, v144
	s_movk_i32 s13, 0x1000
	s_and_b64 vcc, exec, s[10:11]
	s_cselect_b32 s13, s13, 0xfffff000
	v_mfma_f32_32x32x16_bf16 v[2:17], v[54:57], v[130:133], v[2:17]
	s_cbranch_vccnz .Lys3_fwd
	s_nop 6
	global_atomic_add_f32 v78, v34, s[56:57]
	v_mad_i32_i24 v80, s13, 1, v78
	global_atomic_add_f32 v80, v35, s[56:57]
	v_mad_i32_i24 v81, s13, 2, v78
	global_atomic_add_f32 v81, v36, s[56:57]
	v_mad_i32_i24 v79, s13, 3, v78
	global_atomic_add_f32 v79, v37, s[56:57]
	v_mad_i32_i24 v80, s13, 8, v78
	global_atomic_add_f32 v80, v38, s[56:57]
	v_mad_i32_i24 v81, s13, 9, v78
	global_atomic_add_f32 v81, v39, s[56:57]
	v_mad_i32_i24 v79, s13, 10, v78
	global_atomic_add_f32 v79, v40, s[56:57]
	v_mad_i32_i24 v80, s13, 11, v78
	global_atomic_add_f32 v80, v41, s[56:57]
	v_mad_i32_i24 v81, s13, 16, v78
	global_atomic_add_f32 v81, v42, s[56:57]
	v_mad_i32_i24 v79, s13, 17, v78
	global_atomic_add_f32 v79, v43, s[56:57]
	v_mad_i32_i24 v80, s13, 18, v78
	global_atomic_add_f32 v80, v44, s[56:57]
	v_mad_i32_i24 v81, s13, 19, v78
	global_atomic_add_f32 v81, v45, s[56:57]
	v_mad_i32_i24 v79, s13, 24, v78
	global_atomic_add_f32 v79, v46, s[56:57]
	v_mad_i32_i24 v80, s13, 25, v78
	global_atomic_add_f32 v80, v47, s[56:57]
	v_mad_i32_i24 v81, s13, 26, v78
	global_atomic_add_f32 v81, v48, s[56:57]
	v_mad_i32_i24 v79, s13, 27, v78
	global_atomic_add_f32 v79, v49, s[56:57]
	s_branch .Lys3_join
